# norm phase: context-row K-split partial reduction and residual fix-up loads batched (8 in flight)
# baseline (speedup 1.0000x reference)
; __device__ __forceinline__ void phase_norm(CArgs& a, int l, int which) {
;     ...
;                 for (int p = 0; p < npart; ++p)
; #pragma unroll
;                     for (int j = 0; j < 8; ++j) ps[j] += *(const f32x4*)(PART + ((size_t)(p * 32 + b * 8 + j) << 16) + i * 256 + 4 * lane);
.LBB0_320:
	v_lshl_add_u64 v[118:119], v[112:113], 0, s[22:23]
	s_add_u32 s22, s22, 0x800000
	s_addc_u32 s23, s23, 0
	v_add_co_u32_e32 v114, vcc, s82, v118
	s_nop 1
	v_addc_co_u32_e32 v115, vcc, 0, v119, vcc
	global_load_dwordx4 v[156:159], v[114:115], off
	v_add_co_u32_e32 v114, vcc, s83, v118
	s_nop 1
	v_addc_co_u32_e32 v115, vcc, 0, v119, vcc
	global_load_dwordx4 v[160:163], v[114:115], off
	v_add_co_u32_e32 v114, vcc, s84, v118
	s_nop 1
	v_addc_co_u32_e32 v115, vcc, 0, v119, vcc
	global_load_dwordx4 v[164:167], v[114:115], off
	v_add_co_u32_e32 v114, vcc, s85, v118
	s_nop 1
	v_addc_co_u32_e32 v115, vcc, 0, v119, vcc
	global_load_dwordx4 v[168:171], v[114:115], off
	v_add_co_u32_e32 v114, vcc, s86, v118
	s_nop 1
	v_addc_co_u32_e32 v115, vcc, 0, v119, vcc
	global_load_dwordx4 v[172:175], v[114:115], off
	v_add_co_u32_e32 v114, vcc, s87, v118
	s_nop 1
	v_addc_co_u32_e32 v115, vcc, 0, v119, vcc
	global_load_dwordx4 v[176:179], v[114:115], off
	v_add_co_u32_e32 v114, vcc, s88, v118
	s_nop 1
	v_addc_co_u32_e32 v115, vcc, 0, v119, vcc
	global_load_dwordx4 v[180:183], v[114:115], off
	v_add_co_u32_e32 v114, vcc, s89, v118
	s_nop 1
	v_addc_co_u32_e32 v115, vcc, 0, v119, vcc
	global_load_dwordx4 v[184:187], v[114:115], off
	s_waitcnt vmcnt(7)
	v_pk_add_f32 v[56:57], v[56:57], v[156:157]
	v_pk_add_f32 v[110:111], v[110:111], v[158:159]
	s_waitcnt vmcnt(6)
	v_pk_add_f32 v[48:49], v[48:49], v[160:161]
	v_pk_add_f32 v[54:55], v[54:55], v[162:163]
	s_waitcnt vmcnt(5)
	v_pk_add_f32 v[40:41], v[40:41], v[164:165]
	v_pk_add_f32 v[46:47], v[46:47], v[166:167]
	s_waitcnt vmcnt(4)
	v_pk_add_f32 v[32:33], v[32:33], v[168:169]
	v_pk_add_f32 v[38:39], v[38:39], v[170:171]
	s_waitcnt vmcnt(3)
	v_pk_add_f32 v[24:25], v[24:25], v[172:173]
	v_pk_add_f32 v[30:31], v[30:31], v[174:175]
	s_waitcnt vmcnt(2)
	v_pk_add_f32 v[16:17], v[16:17], v[176:177]
	v_pk_add_f32 v[22:23], v[22:23], v[178:179]
	s_waitcnt vmcnt(1)
	v_pk_add_f32 v[8:9], v[8:9], v[180:181]
	v_pk_add_f32 v[14:15], v[14:15], v[182:183]
	s_waitcnt vmcnt(0)
	v_pk_add_f32 v[4:5], v[4:5], v[184:185]
	v_pk_add_f32 v[6:7], v[6:7], v[186:187]
	s_cmp_eq_u32 s18, s22
	s_cbranch_scc0 .LBB0_320
	s_branch .LBB0_322

; __device__ __forceinline__ void phase_norm(CArgs& a, int l, int which) {
;     ...
; #pragma unroll
;                 for (int j = 0; j < 8; ++j) { x[u][j] += *(const f32x4*)(gt + 4 * lane + 256 * j) * ps[j]; *(f32x4*)(XR + (size_t)rr * DM + 4 * lane + 256 * j) = x[u][j]; }
.LBB0_322:
	v_lshlrev_b64 v[112:113], 13, v[66:67]
	v_lshl_add_u64 v[116:117], v[72:73], 0, v[112:113]
	global_load_dwordx4 v[156:159], v[70:71], off
	global_load_dwordx4 v[160:163], v[70:71], off offset:1024
	global_load_dwordx4 v[164:167], v[70:71], off offset:2048
	global_load_dwordx4 v[168:171], v[70:71], off offset:3072
	global_load_dwordx4 v[172:175], v[74:75], off
	global_load_dwordx4 v[176:179], v[76:77], off
	global_load_dwordx4 v[180:183], v[78:79], off
	global_load_dwordx4 v[184:187], v[80:81], off
	v_add_co_u32_e32 v188, vcc, s10, v116
	s_nop 1
	v_addc_co_u32_e32 v189, vcc, 0, v117, vcc
	s_waitcnt vmcnt(7)
	v_pk_fma_f32 v[64:65], v[110:111], v[158:159], v[64:65]
	v_pk_fma_f32 v[62:63], v[56:57], v[156:157], v[62:63]
	global_store_dwordx4 v[116:117], v[62:65], off
	s_waitcnt vmcnt(7)
	v_pk_fma_f32 v[60:61], v[54:55], v[162:163], v[60:61]
	v_pk_fma_f32 v[58:59], v[48:49], v[160:161], v[58:59]
	global_store_dwordx4 v[116:117], v[58:61], off offset:1024
	s_waitcnt vmcnt(7)
	v_pk_fma_f32 v[52:53], v[46:47], v[166:167], v[52:53]
	v_pk_fma_f32 v[50:51], v[40:41], v[164:165], v[50:51]
	global_store_dwordx4 v[116:117], v[50:53], off offset:2048
	s_waitcnt vmcnt(7)
	v_pk_fma_f32 v[44:45], v[38:39], v[170:171], v[44:45]
	v_pk_fma_f32 v[42:43], v[32:33], v[168:169], v[42:43]
	global_store_dwordx4 v[116:117], v[42:45], off offset:3072
	s_waitcnt vmcnt(7)
	v_pk_fma_f32 v[36:37], v[30:31], v[174:175], v[36:37]
	v_pk_fma_f32 v[34:35], v[24:25], v[172:173], v[34:35]
	global_store_dwordx4 v[188:189], v[34:37], off
	s_waitcnt vmcnt(7)
	v_pk_fma_f32 v[28:29], v[22:23], v[178:179], v[28:29]
	v_pk_fma_f32 v[26:27], v[16:17], v[176:177], v[26:27]
	global_store_dwordx4 v[188:189], v[26:29], off offset:1024
	s_waitcnt vmcnt(7)
	v_pk_fma_f32 v[20:21], v[14:15], v[182:183], v[20:21]
	v_pk_fma_f32 v[18:19], v[8:9], v[180:181], v[18:19]
	global_store_dwordx4 v[188:189], v[18:21], off offset:2048
	s_waitcnt vmcnt(7)
	v_pk_fma_f32 v[12:13], v[6:7], v[186:187], v[12:13]
	v_pk_fma_f32 v[10:11], v[4:5], v[184:185], v[10:11]
	global_store_dwordx4 v[188:189], v[10:13], off offset:3072

; __device__ __forceinline__ void phase_norm(CArgs& a, int l, int which) {
;     ...
;                 for (int p = 0; p < npart; ++p)
; #pragma unroll
;                     for (int j = 0; j < 8; ++j) ps[j] += *(const f32x4*)(PART + ((size_t)(p * 32 + b * 8 + j) << 16) + i * 256 + 4 * lane);
.LBB0_334:
	v_lshl_add_u64 v[154:155], v[148:149], 0, s[22:23]
	s_add_u32 s22, s22, 0x800000
	s_addc_u32 s23, s23, 0
	v_add_co_u32_e32 v150, vcc, s82, v154
	s_nop 1
	v_addc_co_u32_e32 v151, vcc, 0, v155, vcc
	global_load_dwordx4 v[156:159], v[150:151], off
	v_add_co_u32_e32 v150, vcc, s83, v154
	s_nop 1
	v_addc_co_u32_e32 v151, vcc, 0, v155, vcc
	global_load_dwordx4 v[160:163], v[150:151], off
	v_add_co_u32_e32 v150, vcc, s84, v154
	s_nop 1
	v_addc_co_u32_e32 v151, vcc, 0, v155, vcc
	global_load_dwordx4 v[164:167], v[150:151], off
	v_add_co_u32_e32 v150, vcc, s85, v154
	s_nop 1
	v_addc_co_u32_e32 v151, vcc, 0, v155, vcc
	global_load_dwordx4 v[168:171], v[150:151], off
	v_add_co_u32_e32 v150, vcc, s86, v154
	s_nop 1
	v_addc_co_u32_e32 v151, vcc, 0, v155, vcc
	global_load_dwordx4 v[172:175], v[150:151], off
	v_add_co_u32_e32 v150, vcc, s87, v154
	s_nop 1
	v_addc_co_u32_e32 v151, vcc, 0, v155, vcc
	global_load_dwordx4 v[176:179], v[150:151], off
	v_add_co_u32_e32 v150, vcc, s88, v154
	s_nop 1
	v_addc_co_u32_e32 v151, vcc, 0, v155, vcc
	global_load_dwordx4 v[180:183], v[150:151], off
	v_add_co_u32_e32 v150, vcc, s89, v154
	s_nop 1
	v_addc_co_u32_e32 v151, vcc, 0, v155, vcc
	global_load_dwordx4 v[184:187], v[150:151], off
	s_waitcnt vmcnt(7)
	v_pk_add_f32 v[144:145], v[144:145], v[156:157]
	v_pk_add_f32 v[146:147], v[146:147], v[158:159]
	s_waitcnt vmcnt(6)
	v_pk_add_f32 v[140:141], v[140:141], v[160:161]
	v_pk_add_f32 v[142:143], v[142:143], v[162:163]
	s_waitcnt vmcnt(5)
	v_pk_add_f32 v[136:137], v[136:137], v[164:165]
	v_pk_add_f32 v[138:139], v[138:139], v[166:167]
	s_waitcnt vmcnt(4)
	v_pk_add_f32 v[132:133], v[132:133], v[168:169]
	v_pk_add_f32 v[134:135], v[134:135], v[170:171]
	s_waitcnt vmcnt(3)
	v_pk_add_f32 v[128:129], v[128:129], v[172:173]
	v_pk_add_f32 v[130:131], v[130:131], v[174:175]
	s_waitcnt vmcnt(2)
	v_pk_add_f32 v[124:125], v[124:125], v[176:177]
	v_pk_add_f32 v[126:127], v[126:127], v[178:179]
	s_waitcnt vmcnt(1)
	v_pk_add_f32 v[120:121], v[120:121], v[180:181]
	v_pk_add_f32 v[122:123], v[122:123], v[182:183]
	s_waitcnt vmcnt(0)
	v_pk_add_f32 v[114:115], v[114:115], v[184:185]
	v_pk_add_f32 v[118:119], v[118:119], v[186:187]
	s_cmp_lg_u32 s18, s22
	s_cbranch_scc1 .LBB0_334
	s_branch .LBB0_336

; __device__ __forceinline__ void phase_norm(CArgs& a, int l, int which) {
;     ...
; #pragma unroll
;                 for (int j = 0; j < 8; ++j) { x[u][j] += *(const f32x4*)(gt + 4 * lane + 256 * j) * ps[j]; *(f32x4*)(XR + (size_t)rr * DM + 4 * lane + 256 * j) = x[u][j]; }
.LBB0_336:
	v_lshlrev_b64 v[116:117], 13, v[116:117]
	v_lshl_add_u64 v[116:117], v[72:73], 0, v[116:117]
	global_load_dwordx4 v[156:159], v[70:71], off
	global_load_dwordx4 v[160:163], v[70:71], off offset:1024
	global_load_dwordx4 v[164:167], v[70:71], off offset:2048
	global_load_dwordx4 v[168:171], v[70:71], off offset:3072
	global_load_dwordx4 v[172:175], v[74:75], off
	global_load_dwordx4 v[176:179], v[76:77], off
	global_load_dwordx4 v[180:183], v[78:79], off
	global_load_dwordx4 v[184:187], v[80:81], off
	v_add_co_u32_e32 v188, vcc, s10, v116
	s_nop 1
	v_addc_co_u32_e32 v189, vcc, 0, v117, vcc
	s_waitcnt vmcnt(7)
	v_pk_fma_f32 v[56:57], v[146:147], v[158:159], v[56:57]
	v_pk_fma_f32 v[54:55], v[144:145], v[156:157], v[54:55]
	global_store_dwordx4 v[116:117], v[54:57], off
	s_waitcnt vmcnt(7)
	v_pk_fma_f32 v[48:49], v[142:143], v[162:163], v[48:49]
	v_pk_fma_f32 v[46:47], v[140:141], v[160:161], v[46:47]
	global_store_dwordx4 v[116:117], v[46:49], off offset:1024
	s_waitcnt vmcnt(7)
	v_pk_fma_f32 v[40:41], v[138:139], v[166:167], v[40:41]
	v_pk_fma_f32 v[38:39], v[136:137], v[164:165], v[38:39]
	global_store_dwordx4 v[116:117], v[38:41], off offset:2048
	s_waitcnt vmcnt(7)
	v_pk_fma_f32 v[32:33], v[134:135], v[170:171], v[32:33]
	v_pk_fma_f32 v[30:31], v[132:133], v[168:169], v[30:31]
	global_store_dwordx4 v[116:117], v[30:33], off offset:3072
	s_waitcnt vmcnt(7)
	v_pk_fma_f32 v[24:25], v[130:131], v[174:175], v[24:25]
	v_pk_fma_f32 v[22:23], v[128:129], v[172:173], v[22:23]
	global_store_dwordx4 v[188:189], v[22:25], off
	s_waitcnt vmcnt(7)
	v_pk_fma_f32 v[16:17], v[126:127], v[178:179], v[16:17]
	v_pk_fma_f32 v[14:15], v[124:125], v[176:177], v[14:15]
	global_store_dwordx4 v[188:189], v[14:17], off offset:1024
	s_waitcnt vmcnt(7)
	v_pk_fma_f32 v[8:9], v[122:123], v[182:183], v[8:9]
	v_pk_fma_f32 v[6:7], v[120:121], v[180:181], v[6:7]
	global_store_dwordx4 v[188:189], v[6:9], off offset:2048
	s_waitcnt vmcnt(7)
	v_pk_fma_f32 v[4:5], v[118:119], v[186:187], v[4:5]
	v_pk_fma_f32 v[2:3], v[114:115], v[184:185], v[2:3]
	global_store_dwordx4 v[188:189], v[2:5], off offset:3072
